# v044 + in-projection epilogue skips the 16 rotary cos/sin default moves per block for column tiles pn > 4 (flag in s99)
# speedup vs baseline: 1.0021x; 1.0005x over previous
;     __device__ __forceinline__ void operator()(const f32x4 (&acc)[2][2][4][2], const Unit& u, int wr, int wc, int fr, int fq) const {
;         const int pn = u.pn, row0 = u.pm * BM + wr * 64 + fr, cl = wc * 32 + 8 * fq;
;         int kind, ldc; bf16_t *b0, *b1;
;         if (pn < 4)       { kind = 0; ldc = 1024; b0 = Q + pn * 256 + cl; b1 = b0 + 128; }
;         else if (pn == 4) { kind = 1; ldc = 128;  b0 = Kb + cl; b1 = Vb + cl; }
;         else if (pn < 9)  { kind = 2; ldc = 1024; b0 = U + (pn - 5) * 256 + cl; b1 = b0 + 128; }
;         else if (pn < 13) { kind = 2; ldc = 1024; b0 = VS + (pn - 9) * 256 + cl; b1 = b0 + 128; }
;         else if (pn < 17) { kind = 3; ldc = 1024; b0 = GA + (pn - 13) * 256 + cl; b1 = b0 + 128; }
;         else              { kind = 3; ldc = 1024; b0 = GB + (pn - 17) * 256 + cl; b1 = b0 + 128; }
;         const bool ropelane = ((wc & 1) == 0) && (fq < 2);
.LBB0_193:
	s_cmp_lt_i32 s16, 4
	s_cselect_b64 s[10:11], -1, 0
	s_cmp_gt_u32 s16, 4
	s_cselect_b32 s99, 1, 0
	s_cmp_gt_i32 s16, 3
	s_cselect_b64 s[96:97], -1, 0
	s_mov_b64 s[14:15], -1
	s_and_b64 vcc, exec, s[96:97]
	s_cbranch_vccz .LBB0_207
	s_cmp_eq_u32 s16, 4
	s_mov_b64 s[14:15], 0
	s_cbranch_scc1 .LBB0_437
	s_lshl_b32 s30, s16, 8
	s_cmp_gt_u32 s16, 8
	s_mov_b64 s[20:21], -1
	s_cbranch_scc0 .LBB0_204
	s_mov_b64 s[88:89], -1
	s_cmp_gt_u32 s16, 12
	s_mov_b64 s[18:19], -1
	s_cbranch_scc0 .LBB0_202
	s_cmp_gt_u32 s16, 16
	s_cbranch_scc0 .LBB0_199
	s_add_i32 s18, s30, 0xffffef00
	s_mov_b32 s19, s31
	v_lshl_add_u64 v[180:181], s[18:19], 1, v[162:163]
	v_lshl_add_u64 v[178:179], v[180:181], 0, s[58:59]
	s_mov_b64 s[18:19], 0

;     __device__ __forceinline__ void operator()(const f32x4 (&acc)[2][2][4][2], const Unit& u, int wr, int wc, int fr, int fq) const {
;     ...
;                 const int row = row0 + ai * HALF + m * 16;
;                 float ps = 0.f, pss = 0.f;
;                 f32x4 c0 = {1.f, 1.f, 1.f, 1.f}, c1 = c0, s0 = {0.f, 0.f, 0.f, 0.f}, s1 = s0;
;                 if (kind <= 1 && ropelane) { const f32x4* rp = (const f32x4*)(rope + (size_t)row * 16); c0 = rp[0]; c1 = rp[1]; s0 = rp[2]; s1 = rp[3]; }
.LBB0_209:
	v_lshl_add_u32 v182, s12, 8, v157
	s_and_b64 s[12:13], s[54:55], s[20:21]
	s_and_b64 s[94:95], s[12:13], s[4:5]
	v_ashrrev_i32_e32 v183, 31, v182
	s_cmp_lg_u32 s99, 0
	s_cbranch_scc1 .Lropedef_0_0
	v_mov_b32_e32 v134, 1.0
	v_mov_b32_e32 v130, 0
	v_mov_b32_e32 v131, v130
	v_mov_b32_e32 v132, v130
	v_mov_b32_e32 v133, v130
	v_mov_b32_e32 v138, v130
	v_mov_b32_e32 v139, v130
	v_mov_b32_e32 v140, v130
	v_mov_b32_e32 v141, v130
	v_mov_b32_e32 v135, v134
	v_mov_b32_e32 v136, v134
	v_mov_b32_e32 v137, v134
	v_mov_b32_e32 v142, v134
	v_mov_b32_e32 v143, v134
	v_mov_b32_e32 v144, v134
	v_mov_b32_e32 v145, v134
.Lropedef_0_0:
	s_and_saveexec_b64 s[12:13], s[94:95]
	s_cbranch_execz .LBB0_211
	v_lshlrev_b64 v[130:131], 6, v[182:183]
	v_lshl_add_u64 v[142:143], s[44:45], 0, v[130:131]
	global_load_dwordx4 v[130:133], v[142:143], off offset:48
	global_load_dwordx4 v[138:141], v[142:143], off offset:32
	global_load_dwordx4 v[134:137], v[142:143], off offset:16
	s_nop 0
	global_load_dwordx4 v[142:145], v[142:143], off

;     __device__ __forceinline__ void operator()(const f32x4 (&acc)[2][2][4][2], const Unit& u, int wr, int wc, int fr, int fq) const {
;     ...
;                 const int row = row0 + ai * HALF + m * 16;
;                 float ps = 0.f, pss = 0.f;
;                 f32x4 c0 = {1.f, 1.f, 1.f, 1.f}, c1 = c0, s0 = {0.f, 0.f, 0.f, 0.f}, s1 = s0;
;                 if (kind <= 1 && ropelane) { const f32x4* rp = (const f32x4*)(rope + (size_t)row * 16); c0 = rp[0]; c1 = rp[1]; s0 = rp[2]; s1 = rp[3]; }
.LBB0_237:
	s_waitcnt vmcnt(0)
	v_or_b32_e32 v130, 16, v182
	v_ashrrev_i32_e32 v131, 31, v130
	s_waitcnt lgkmcnt(1)
	s_waitcnt lgkmcnt(0)
	s_cmp_lg_u32 s99, 0
	s_cbranch_scc1 .Lropedef_0_1
	v_mov_b32_e32 v118, 1.0
	v_mov_b32_e32 v114, 0
	v_mov_b32_e32 v115, v114
	v_mov_b32_e32 v116, v114
	v_mov_b32_e32 v117, v114
	v_mov_b32_e32 v122, v114
	v_mov_b32_e32 v123, v114
	v_mov_b32_e32 v124, v114
	v_mov_b32_e32 v125, v114
	v_mov_b32_e32 v119, v118
	v_mov_b32_e32 v120, v118
	v_mov_b32_e32 v121, v118
	v_mov_b32_e32 v126, v118
	v_mov_b32_e32 v127, v118
	v_mov_b32_e32 v128, v118
	v_mov_b32_e32 v129, v118
.Lropedef_0_1:
	s_and_saveexec_b64 s[18:19], s[94:95]
	s_cbranch_execz .LBB0_239
	v_lshlrev_b64 v[114:115], 6, v[130:131]
	v_lshl_add_u64 v[126:127], s[44:45], 0, v[114:115]
	global_load_dwordx4 v[114:117], v[126:127], off offset:48
	global_load_dwordx4 v[122:125], v[126:127], off offset:32
	global_load_dwordx4 v[118:121], v[126:127], off offset:16
	s_nop 0
	global_load_dwordx4 v[126:129], v[126:127], off

;     __device__ __forceinline__ void operator()(const f32x4 (&acc)[2][2][4][2], const Unit& u, int wr, int wc, int fr, int fq) const {
;     ...
;                 const int row = row0 + ai * HALF + m * 16;
;                 float ps = 0.f, pss = 0.f;
;                 f32x4 c0 = {1.f, 1.f, 1.f, 1.f}, c1 = c0, s0 = {0.f, 0.f, 0.f, 0.f}, s1 = s0;
;                 if (kind <= 1 && ropelane) { const f32x4* rp = (const f32x4*)(rope + (size_t)row * 16); c0 = rp[0]; c1 = rp[1]; s0 = rp[2]; s1 = rp[3]; }
.LBB0_266:
	s_waitcnt vmcnt(5)
	v_or_b32_e32 v114, 32, v182
	v_ashrrev_i32_e32 v115, 31, v114
	s_waitcnt lgkmcnt(1)
	s_waitcnt lgkmcnt(0)
	s_cmp_lg_u32 s99, 0
	s_cbranch_scc1 .Lropedef_0_2
	v_mov_b32_e32 v102, 1.0
	v_mov_b32_e32 v98, 0
	v_mov_b32_e32 v99, v98
	v_mov_b32_e32 v100, v98
	v_mov_b32_e32 v101, v98
	v_mov_b32_e32 v106, v98
	v_mov_b32_e32 v107, v98
	v_mov_b32_e32 v108, v98
	v_mov_b32_e32 v109, v98
	v_mov_b32_e32 v103, v102
	v_mov_b32_e32 v104, v102
	v_mov_b32_e32 v105, v102
	v_mov_b32_e32 v110, v102
	v_mov_b32_e32 v111, v102
	v_mov_b32_e32 v112, v102
	v_mov_b32_e32 v113, v102
.Lropedef_0_2:
	s_and_saveexec_b64 s[20:21], s[94:95]
	s_cbranch_execz .LBB0_268
	v_lshlrev_b64 v[98:99], 6, v[114:115]
	v_lshl_add_u64 v[110:111], s[44:45], 0, v[98:99]
	global_load_dwordx4 v[98:101], v[110:111], off offset:48
	global_load_dwordx4 v[106:109], v[110:111], off offset:32
	global_load_dwordx4 v[102:105], v[110:111], off offset:16
	s_nop 0
	global_load_dwordx4 v[110:113], v[110:111], off

;     __device__ __forceinline__ void operator()(const f32x4 (&acc)[2][2][4][2], const Unit& u, int wr, int wc, int fr, int fq) const {
;     ...
;                 const int row = row0 + ai * HALF + m * 16;
;                 float ps = 0.f, pss = 0.f;
;                 f32x4 c0 = {1.f, 1.f, 1.f, 1.f}, c1 = c0, s0 = {0.f, 0.f, 0.f, 0.f}, s1 = s0;
;                 if (kind <= 1 && ropelane) { const f32x4* rp = (const f32x4*)(rope + (size_t)row * 16); c0 = rp[0]; c1 = rp[1]; s0 = rp[2]; s1 = rp[3]; }
.LBB0_293:
	v_or_b32_e32 v98, 48, v182
	v_ashrrev_i32_e32 v99, 31, v98
	s_waitcnt lgkmcnt(1)
	s_waitcnt lgkmcnt(0)
	s_cmp_lg_u32 s99, 0
	s_cbranch_scc1 .Lropedef_0_3
	v_mov_b32_e32 v86, 1.0
	v_mov_b32_e32 v82, 0
	v_mov_b32_e32 v83, v82
	v_mov_b32_e32 v84, v82
	v_mov_b32_e32 v85, v82
	v_mov_b32_e32 v90, v82
	v_mov_b32_e32 v91, v82
	v_mov_b32_e32 v92, v82
	v_mov_b32_e32 v93, v82
	v_mov_b32_e32 v87, v86
	v_mov_b32_e32 v88, v86
	v_mov_b32_e32 v89, v86
	v_mov_b32_e32 v94, v86
	v_mov_b32_e32 v95, v86
	v_mov_b32_e32 v96, v86
	v_mov_b32_e32 v97, v86
.Lropedef_0_3:
	s_and_saveexec_b64 s[20:21], s[94:95]
	s_cbranch_execz .LBB0_295
	v_lshlrev_b64 v[82:83], 6, v[98:99]
	v_lshl_add_u64 v[94:95], s[44:45], 0, v[82:83]
	global_load_dwordx4 v[82:85], v[94:95], off offset:48
	global_load_dwordx4 v[90:93], v[94:95], off offset:32
	global_load_dwordx4 v[86:89], v[94:95], off offset:16
	s_nop 0
	global_load_dwordx4 v[94:97], v[94:95], off

;     __device__ __forceinline__ void operator()(const f32x4 (&acc)[2][2][4][2], const Unit& u, int wr, int wc, int fr, int fq) const {
;     ...
;                 const int row = row0 + ai * HALF + m * 16;
;                 float ps = 0.f, pss = 0.f;
;                 f32x4 c0 = {1.f, 1.f, 1.f, 1.f}, c1 = c0, s0 = {0.f, 0.f, 0.f, 0.f}, s1 = s0;
;                 if (kind <= 1 && ropelane) { const f32x4* rp = (const f32x4*)(rope + (size_t)row * 16); c0 = rp[0]; c1 = rp[1]; s0 = rp[2]; s1 = rp[3]; }
.LBB0_320:
	v_add_u32_e32 v82, 0x80, v182
	v_ashrrev_i32_e32 v83, 31, v82
	s_waitcnt lgkmcnt(1)
	s_waitcnt lgkmcnt(0)
	s_cmp_lg_u32 s99, 0
	s_cbranch_scc1 .Lropedef_0_4
	v_mov_b32_e32 v70, 1.0
	v_mov_b32_e32 v66, 0
	v_mov_b32_e32 v67, v66
	v_mov_b32_e32 v68, v66
	v_mov_b32_e32 v69, v66
	v_mov_b32_e32 v74, v66
	v_mov_b32_e32 v75, v66
	v_mov_b32_e32 v76, v66
	v_mov_b32_e32 v77, v66
	v_mov_b32_e32 v71, v70
	v_mov_b32_e32 v72, v70
	v_mov_b32_e32 v73, v70
	v_mov_b32_e32 v78, v70
	v_mov_b32_e32 v79, v70
	v_mov_b32_e32 v80, v70
	v_mov_b32_e32 v81, v70
.Lropedef_0_4:
	s_and_saveexec_b64 s[20:21], s[94:95]
	s_cbranch_execz .LBB0_322
	v_lshlrev_b64 v[66:67], 6, v[82:83]
	v_lshl_add_u64 v[78:79], s[44:45], 0, v[66:67]
	global_load_dwordx4 v[66:69], v[78:79], off offset:48
	global_load_dwordx4 v[74:77], v[78:79], off offset:32
	global_load_dwordx4 v[70:73], v[78:79], off offset:16
	s_nop 0
	global_load_dwordx4 v[78:81], v[78:79], off

;     __device__ __forceinline__ void operator()(const f32x4 (&acc)[2][2][4][2], const Unit& u, int wr, int wc, int fr, int fq) const {
;     ...
;                 const int row = row0 + ai * HALF + m * 16;
;                 float ps = 0.f, pss = 0.f;
;                 f32x4 c0 = {1.f, 1.f, 1.f, 1.f}, c1 = c0, s0 = {0.f, 0.f, 0.f, 0.f}, s1 = s0;
;                 if (kind <= 1 && ropelane) { const f32x4* rp = (const f32x4*)(rope + (size_t)row * 16); c0 = rp[0]; c1 = rp[1]; s0 = rp[2]; s1 = rp[3]; }
.LBB0_347:
	v_add_u32_e32 v66, 0x90, v182
	v_ashrrev_i32_e32 v67, 31, v66
	s_waitcnt lgkmcnt(1)
	s_waitcnt lgkmcnt(0)
	s_cmp_lg_u32 s99, 0
	s_cbranch_scc1 .Lropedef_0_5
	v_mov_b32_e32 v54, 1.0
	v_mov_b32_e32 v50, 0
	v_mov_b32_e32 v51, v50
	v_mov_b32_e32 v52, v50
	v_mov_b32_e32 v53, v50
	v_mov_b32_e32 v58, v50
	v_mov_b32_e32 v59, v50
	v_mov_b32_e32 v60, v50
	v_mov_b32_e32 v61, v50
	v_mov_b32_e32 v55, v54
	v_mov_b32_e32 v56, v54
	v_mov_b32_e32 v57, v54
	v_mov_b32_e32 v62, v54
	v_mov_b32_e32 v63, v54
	v_mov_b32_e32 v64, v54
	v_mov_b32_e32 v65, v54
.Lropedef_0_5:
	s_and_saveexec_b64 s[20:21], s[94:95]
	s_cbranch_execz .LBB0_349
	v_lshlrev_b64 v[50:51], 6, v[66:67]
	v_lshl_add_u64 v[62:63], s[44:45], 0, v[50:51]
	global_load_dwordx4 v[50:53], v[62:63], off offset:48
	global_load_dwordx4 v[58:61], v[62:63], off offset:32
	global_load_dwordx4 v[54:57], v[62:63], off offset:16
	s_nop 0
	global_load_dwordx4 v[62:65], v[62:63], off

;     __device__ __forceinline__ void operator()(const f32x4 (&acc)[2][2][4][2], const Unit& u, int wr, int wc, int fr, int fq) const {
;     ...
;                 const int row = row0 + ai * HALF + m * 16;
;                 float ps = 0.f, pss = 0.f;
;                 f32x4 c0 = {1.f, 1.f, 1.f, 1.f}, c1 = c0, s0 = {0.f, 0.f, 0.f, 0.f}, s1 = s0;
;                 if (kind <= 1 && ropelane) { const f32x4* rp = (const f32x4*)(rope + (size_t)row * 16); c0 = rp[0]; c1 = rp[1]; s0 = rp[2]; s1 = rp[3]; }
.LBB0_374:
	v_add_u32_e32 v50, 0xa0, v182
	v_ashrrev_i32_e32 v51, 31, v50
	s_waitcnt lgkmcnt(1)
	s_waitcnt lgkmcnt(0)
	s_cmp_lg_u32 s99, 0
	s_cbranch_scc1 .Lropedef_0_6
	v_mov_b32_e32 v38, 1.0
	v_mov_b32_e32 v34, 0
	v_mov_b32_e32 v35, v34
	v_mov_b32_e32 v36, v34
	v_mov_b32_e32 v37, v34
	v_mov_b32_e32 v42, v34
	v_mov_b32_e32 v43, v34
	v_mov_b32_e32 v44, v34
	v_mov_b32_e32 v45, v34
	v_mov_b32_e32 v39, v38
	v_mov_b32_e32 v40, v38
	v_mov_b32_e32 v41, v38
	v_mov_b32_e32 v46, v38
	v_mov_b32_e32 v47, v38
	v_mov_b32_e32 v48, v38
	v_mov_b32_e32 v49, v38
.Lropedef_0_6:
	s_and_saveexec_b64 s[20:21], s[94:95]
	s_cbranch_execz .LBB0_376
	v_lshlrev_b64 v[34:35], 6, v[50:51]
	v_lshl_add_u64 v[46:47], s[44:45], 0, v[34:35]
	global_load_dwordx4 v[34:37], v[46:47], off offset:48
	global_load_dwordx4 v[42:45], v[46:47], off offset:32
	global_load_dwordx4 v[38:41], v[46:47], off offset:16
	s_nop 0
	global_load_dwordx4 v[46:49], v[46:47], off

;     __device__ __forceinline__ void operator()(const f32x4 (&acc)[2][2][4][2], const Unit& u, int wr, int wc, int fr, int fq) const {
;     ...
;                 const int row = row0 + ai * HALF + m * 16;
;                 float ps = 0.f, pss = 0.f;
;                 f32x4 c0 = {1.f, 1.f, 1.f, 1.f}, c1 = c0, s0 = {0.f, 0.f, 0.f, 0.f}, s1 = s0;
;                 if (kind <= 1 && ropelane) { const f32x4* rp = (const f32x4*)(rope + (size_t)row * 16); c0 = rp[0]; c1 = rp[1]; s0 = rp[2]; s1 = rp[3]; }
.LBB0_401:
	v_add_u32_e32 v34, 0xb0, v182
	v_ashrrev_i32_e32 v35, 31, v34
	s_waitcnt lgkmcnt(1)
	s_waitcnt lgkmcnt(0)
	s_cmp_lg_u32 s99, 0
	s_cbranch_scc1 .Lropedef_0_7
	v_mov_b32_e32 v22, 1.0
	v_mov_b32_e32 v18, 0
	v_mov_b32_e32 v19, v18
	v_mov_b32_e32 v20, v18
	v_mov_b32_e32 v21, v18
	v_mov_b32_e32 v26, v18
	v_mov_b32_e32 v27, v18
	v_mov_b32_e32 v28, v18
	v_mov_b32_e32 v29, v18
	v_mov_b32_e32 v23, v22
	v_mov_b32_e32 v24, v22
	v_mov_b32_e32 v25, v22
	v_mov_b32_e32 v30, v22
	v_mov_b32_e32 v31, v22
	v_mov_b32_e32 v32, v22
	v_mov_b32_e32 v33, v22
.Lropedef_0_7:
	s_and_saveexec_b64 s[20:21], s[94:95]
	s_cbranch_execz .LBB0_403
	v_lshlrev_b64 v[18:19], 6, v[34:35]
	v_lshl_add_u64 v[30:31], s[44:45], 0, v[18:19]
	global_load_dwordx4 v[18:21], v[30:31], off offset:48
	global_load_dwordx4 v[26:29], v[30:31], off offset:32
	global_load_dwordx4 v[22:25], v[30:31], off offset:16
	s_nop 0
	global_load_dwordx4 v[30:33], v[30:31], off

;     __device__ __forceinline__ void operator()(const f32x4 (&acc)[2][2][4][2], const Unit& u, int wr, int wc, int fr, int fq) const {
;         const int pn = u.pn, row0 = u.pm * BM + wr * 64 + fr, cl = wc * 32 + 8 * fq;
;         int kind, ldc; bf16_t *b0, *b1;
;         if (pn < 4)       { kind = 0; ldc = 1024; b0 = Q + pn * 256 + cl; b1 = b0 + 128; }
;         else if (pn == 4) { kind = 1; ldc = 128;  b0 = Kb + cl; b1 = Vb + cl; }
;         else if (pn < 9)  { kind = 2; ldc = 1024; b0 = U + (pn - 5) * 256 + cl; b1 = b0 + 128; }
;         else if (pn < 13) { kind = 2; ldc = 1024; b0 = VS + (pn - 9) * 256 + cl; b1 = b0 + 128; }
;         else if (pn < 17) { kind = 3; ldc = 1024; b0 = GA + (pn - 13) * 256 + cl; b1 = b0 + 128; }
;         else              { kind = 3; ldc = 1024; b0 = GB + (pn - 17) * 256 + cl; b1 = b0 + 128; }
;         const bool ropelane = ((wc & 1) == 0) && (fq < 2);
.LBB0_1096:
	s_cmp_lt_i32 s18, 4
	s_cselect_b64 s[12:13], -1, 0
	s_cmp_gt_u32 s18, 4
	s_cselect_b32 s99, 1, 0
	s_cmp_gt_i32 s18, 3
	s_cselect_b64 s[94:95], -1, 0
	s_mov_b64 s[16:17], -1
	s_and_b64 vcc, exec, s[94:95]
	s_cbranch_vccz .LBB0_1110
	s_cmp_eq_u32 s18, 4
	s_mov_b64 s[16:17], 0
	s_cbranch_scc1 .LBB0_1340
	s_lshl_b32 s30, s18, 8
	s_cmp_gt_u32 s18, 8
	s_mov_b64 s[22:23], -1
	s_cbranch_scc0 .LBB0_1107
	s_mov_b64 s[86:87], -1
	s_cmp_gt_u32 s18, 12
	s_mov_b64 s[20:21], -1
	s_cbranch_scc0 .LBB0_1105
	s_cmp_gt_u32 s18, 16
	s_cbranch_scc0 .LBB0_1102
	s_add_i32 s20, s30, 0xffffef00
	s_mov_b32 s21, s31
	v_lshl_add_u64 v[178:179], s[20:21], 1, v[162:163]
	v_lshl_add_u64 v[176:177], v[178:179], 0, s[56:57]
	s_mov_b64 s[20:21], 0

;     __device__ __forceinline__ void operator()(const f32x4 (&acc)[2][2][4][2], const Unit& u, int wr, int wc, int fr, int fq) const {
;     ...
;                 const int row = row0 + ai * HALF + m * 16;
;                 float ps = 0.f, pss = 0.f;
;                 f32x4 c0 = {1.f, 1.f, 1.f, 1.f}, c1 = c0, s0 = {0.f, 0.f, 0.f, 0.f}, s1 = s0;
;                 if (kind <= 1 && ropelane) { const f32x4* rp = (const f32x4*)(rope + (size_t)row * 16); c0 = rp[0]; c1 = rp[1]; s0 = rp[2]; s1 = rp[3]; }
.LBB0_1112:
	v_lshl_add_u32 v180, s14, 8, v157
	s_and_b64 s[14:15], s[52:53], s[22:23]
	s_and_b64 s[92:93], s[14:15], s[8:9]
	v_ashrrev_i32_e32 v181, 31, v180
	s_cmp_lg_u32 s99, 0
	s_cbranch_scc1 .Lropedef_1_0
	v_mov_b32_e32 v134, 1.0
	v_mov_b32_e32 v130, 0
	v_mov_b32_e32 v131, v130
	v_mov_b32_e32 v132, v130
	v_mov_b32_e32 v133, v130
	v_mov_b32_e32 v138, v130
	v_mov_b32_e32 v139, v130
	v_mov_b32_e32 v140, v130
	v_mov_b32_e32 v141, v130
	v_mov_b32_e32 v135, v134
	v_mov_b32_e32 v136, v134
	v_mov_b32_e32 v137, v134
	v_mov_b32_e32 v142, v134
	v_mov_b32_e32 v143, v134
	v_mov_b32_e32 v144, v134
	v_mov_b32_e32 v145, v134
.Lropedef_1_0:
	s_and_saveexec_b64 s[14:15], s[92:93]
	s_cbranch_execz .LBB0_1114
	v_lshlrev_b64 v[130:131], 6, v[180:181]
	v_lshl_add_u64 v[142:143], s[40:41], 0, v[130:131]
	global_load_dwordx4 v[130:133], v[142:143], off offset:48
	global_load_dwordx4 v[138:141], v[142:143], off offset:32
	global_load_dwordx4 v[134:137], v[142:143], off offset:16
	s_nop 0
	global_load_dwordx4 v[142:145], v[142:143], off

;     __device__ __forceinline__ void operator()(const f32x4 (&acc)[2][2][4][2], const Unit& u, int wr, int wc, int fr, int fq) const {
;     ...
;                 const int row = row0 + ai * HALF + m * 16;
;                 float ps = 0.f, pss = 0.f;
;                 f32x4 c0 = {1.f, 1.f, 1.f, 1.f}, c1 = c0, s0 = {0.f, 0.f, 0.f, 0.f}, s1 = s0;
;                 if (kind <= 1 && ropelane) { const f32x4* rp = (const f32x4*)(rope + (size_t)row * 16); c0 = rp[0]; c1 = rp[1]; s0 = rp[2]; s1 = rp[3]; }
.LBB0_1140:
	s_waitcnt vmcnt(0)
	v_or_b32_e32 v130, 16, v180
	v_ashrrev_i32_e32 v131, 31, v130
	s_waitcnt lgkmcnt(1)
	s_waitcnt lgkmcnt(0)
	s_cmp_lg_u32 s99, 0
	s_cbranch_scc1 .Lropedef_1_1
	v_mov_b32_e32 v118, 1.0
	v_mov_b32_e32 v114, 0
	v_mov_b32_e32 v115, v114
	v_mov_b32_e32 v116, v114
	v_mov_b32_e32 v117, v114
	v_mov_b32_e32 v122, v114
	v_mov_b32_e32 v123, v114
	v_mov_b32_e32 v124, v114
	v_mov_b32_e32 v125, v114
	v_mov_b32_e32 v119, v118
	v_mov_b32_e32 v120, v118
	v_mov_b32_e32 v121, v118
	v_mov_b32_e32 v126, v118
	v_mov_b32_e32 v127, v118
	v_mov_b32_e32 v128, v118
	v_mov_b32_e32 v129, v118
.Lropedef_1_1:
	s_and_saveexec_b64 s[20:21], s[92:93]
	s_cbranch_execz .LBB0_1142
	v_lshlrev_b64 v[114:115], 6, v[130:131]
	v_lshl_add_u64 v[126:127], s[40:41], 0, v[114:115]
	global_load_dwordx4 v[114:117], v[126:127], off offset:48
	global_load_dwordx4 v[122:125], v[126:127], off offset:32
	global_load_dwordx4 v[118:121], v[126:127], off offset:16
	s_nop 0
	global_load_dwordx4 v[126:129], v[126:127], off

;     __device__ __forceinline__ void operator()(const f32x4 (&acc)[2][2][4][2], const Unit& u, int wr, int wc, int fr, int fq) const {
;     ...
;                 const int row = row0 + ai * HALF + m * 16;
;                 float ps = 0.f, pss = 0.f;
;                 f32x4 c0 = {1.f, 1.f, 1.f, 1.f}, c1 = c0, s0 = {0.f, 0.f, 0.f, 0.f}, s1 = s0;
;                 if (kind <= 1 && ropelane) { const f32x4* rp = (const f32x4*)(rope + (size_t)row * 16); c0 = rp[0]; c1 = rp[1]; s0 = rp[2]; s1 = rp[3]; }
.LBB0_1169:
	s_waitcnt vmcnt(5)
	v_or_b32_e32 v114, 32, v180
	v_ashrrev_i32_e32 v115, 31, v114
	s_waitcnt lgkmcnt(1)
	s_waitcnt lgkmcnt(0)
	s_cmp_lg_u32 s99, 0
	s_cbranch_scc1 .Lropedef_1_2
	v_mov_b32_e32 v102, 1.0
	v_mov_b32_e32 v98, 0
	v_mov_b32_e32 v99, v98
	v_mov_b32_e32 v100, v98
	v_mov_b32_e32 v101, v98
	v_mov_b32_e32 v106, v98
	v_mov_b32_e32 v107, v98
	v_mov_b32_e32 v108, v98
	v_mov_b32_e32 v109, v98
	v_mov_b32_e32 v103, v102
	v_mov_b32_e32 v104, v102
	v_mov_b32_e32 v105, v102
	v_mov_b32_e32 v110, v102
	v_mov_b32_e32 v111, v102
	v_mov_b32_e32 v112, v102
	v_mov_b32_e32 v113, v102
.Lropedef_1_2:
	s_and_saveexec_b64 s[22:23], s[92:93]
	s_cbranch_execz .LBB0_1171
	v_lshlrev_b64 v[98:99], 6, v[114:115]
	v_lshl_add_u64 v[110:111], s[40:41], 0, v[98:99]
	global_load_dwordx4 v[98:101], v[110:111], off offset:48
	global_load_dwordx4 v[106:109], v[110:111], off offset:32
	global_load_dwordx4 v[102:105], v[110:111], off offset:16
	s_nop 0
	global_load_dwordx4 v[110:113], v[110:111], off

;     __device__ __forceinline__ void operator()(const f32x4 (&acc)[2][2][4][2], const Unit& u, int wr, int wc, int fr, int fq) const {
;     ...
;                 const int row = row0 + ai * HALF + m * 16;
;                 float ps = 0.f, pss = 0.f;
;                 f32x4 c0 = {1.f, 1.f, 1.f, 1.f}, c1 = c0, s0 = {0.f, 0.f, 0.f, 0.f}, s1 = s0;
;                 if (kind <= 1 && ropelane) { const f32x4* rp = (const f32x4*)(rope + (size_t)row * 16); c0 = rp[0]; c1 = rp[1]; s0 = rp[2]; s1 = rp[3]; }
.LBB0_1196:
	v_or_b32_e32 v98, 48, v180
	v_ashrrev_i32_e32 v99, 31, v98
	s_waitcnt lgkmcnt(1)
	s_waitcnt lgkmcnt(0)
	s_cmp_lg_u32 s99, 0
	s_cbranch_scc1 .Lropedef_1_3
	v_mov_b32_e32 v86, 1.0
	v_mov_b32_e32 v82, 0
	v_mov_b32_e32 v83, v82
	v_mov_b32_e32 v84, v82
	v_mov_b32_e32 v85, v82
	v_mov_b32_e32 v90, v82
	v_mov_b32_e32 v91, v82
	v_mov_b32_e32 v92, v82
	v_mov_b32_e32 v93, v82
	v_mov_b32_e32 v87, v86
	v_mov_b32_e32 v88, v86
	v_mov_b32_e32 v89, v86
	v_mov_b32_e32 v94, v86
	v_mov_b32_e32 v95, v86
	v_mov_b32_e32 v96, v86
	v_mov_b32_e32 v97, v86
.Lropedef_1_3:
	s_and_saveexec_b64 s[22:23], s[92:93]
	s_cbranch_execz .LBB0_1198
	v_lshlrev_b64 v[82:83], 6, v[98:99]
	v_lshl_add_u64 v[94:95], s[40:41], 0, v[82:83]
	global_load_dwordx4 v[82:85], v[94:95], off offset:48
	global_load_dwordx4 v[90:93], v[94:95], off offset:32
	global_load_dwordx4 v[86:89], v[94:95], off offset:16
	s_nop 0
	global_load_dwordx4 v[94:97], v[94:95], off

;     __device__ __forceinline__ void operator()(const f32x4 (&acc)[2][2][4][2], const Unit& u, int wr, int wc, int fr, int fq) const {
;     ...
;                 const int row = row0 + ai * HALF + m * 16;
;                 float ps = 0.f, pss = 0.f;
;                 f32x4 c0 = {1.f, 1.f, 1.f, 1.f}, c1 = c0, s0 = {0.f, 0.f, 0.f, 0.f}, s1 = s0;
;                 if (kind <= 1 && ropelane) { const f32x4* rp = (const f32x4*)(rope + (size_t)row * 16); c0 = rp[0]; c1 = rp[1]; s0 = rp[2]; s1 = rp[3]; }
.LBB0_1223:
	v_add_u32_e32 v82, 0x80, v180
	v_ashrrev_i32_e32 v83, 31, v82
	s_waitcnt lgkmcnt(1)
	s_waitcnt lgkmcnt(0)
	s_cmp_lg_u32 s99, 0
	s_cbranch_scc1 .Lropedef_1_4
	v_mov_b32_e32 v70, 1.0
	v_mov_b32_e32 v66, 0
	v_mov_b32_e32 v67, v66
	v_mov_b32_e32 v68, v66
	v_mov_b32_e32 v69, v66
	v_mov_b32_e32 v74, v66
	v_mov_b32_e32 v75, v66
	v_mov_b32_e32 v76, v66
	v_mov_b32_e32 v77, v66
	v_mov_b32_e32 v71, v70
	v_mov_b32_e32 v72, v70
	v_mov_b32_e32 v73, v70
	v_mov_b32_e32 v78, v70
	v_mov_b32_e32 v79, v70
	v_mov_b32_e32 v80, v70
	v_mov_b32_e32 v81, v70
.Lropedef_1_4:
	s_and_saveexec_b64 s[22:23], s[92:93]
	s_cbranch_execz .LBB0_1225
	v_lshlrev_b64 v[66:67], 6, v[82:83]
	v_lshl_add_u64 v[78:79], s[40:41], 0, v[66:67]
	global_load_dwordx4 v[66:69], v[78:79], off offset:48
	global_load_dwordx4 v[74:77], v[78:79], off offset:32
	global_load_dwordx4 v[70:73], v[78:79], off offset:16
	s_nop 0
	global_load_dwordx4 v[78:81], v[78:79], off

;     __device__ __forceinline__ void operator()(const f32x4 (&acc)[2][2][4][2], const Unit& u, int wr, int wc, int fr, int fq) const {
;     ...
;                 const int row = row0 + ai * HALF + m * 16;
;                 float ps = 0.f, pss = 0.f;
;                 f32x4 c0 = {1.f, 1.f, 1.f, 1.f}, c1 = c0, s0 = {0.f, 0.f, 0.f, 0.f}, s1 = s0;
;                 if (kind <= 1 && ropelane) { const f32x4* rp = (const f32x4*)(rope + (size_t)row * 16); c0 = rp[0]; c1 = rp[1]; s0 = rp[2]; s1 = rp[3]; }
.LBB0_1250:
	v_add_u32_e32 v66, 0x90, v180
	v_ashrrev_i32_e32 v67, 31, v66
	s_waitcnt lgkmcnt(1)
	s_waitcnt lgkmcnt(0)
	s_cmp_lg_u32 s99, 0
	s_cbranch_scc1 .Lropedef_1_5
	v_mov_b32_e32 v54, 1.0
	v_mov_b32_e32 v50, 0
	v_mov_b32_e32 v51, v50
	v_mov_b32_e32 v52, v50
	v_mov_b32_e32 v53, v50
	v_mov_b32_e32 v58, v50
	v_mov_b32_e32 v59, v50
	v_mov_b32_e32 v60, v50
	v_mov_b32_e32 v61, v50
	v_mov_b32_e32 v55, v54
	v_mov_b32_e32 v56, v54
	v_mov_b32_e32 v57, v54
	v_mov_b32_e32 v62, v54
	v_mov_b32_e32 v63, v54
	v_mov_b32_e32 v64, v54
	v_mov_b32_e32 v65, v54
.Lropedef_1_5:
	s_and_saveexec_b64 s[22:23], s[92:93]
	s_cbranch_execz .LBB0_1252
	v_lshlrev_b64 v[50:51], 6, v[66:67]
	v_lshl_add_u64 v[62:63], s[40:41], 0, v[50:51]
	global_load_dwordx4 v[50:53], v[62:63], off offset:48
	global_load_dwordx4 v[58:61], v[62:63], off offset:32
	global_load_dwordx4 v[54:57], v[62:63], off offset:16
	s_nop 0
	global_load_dwordx4 v[62:65], v[62:63], off

;     __device__ __forceinline__ void operator()(const f32x4 (&acc)[2][2][4][2], const Unit& u, int wr, int wc, int fr, int fq) const {
;     ...
;                 const int row = row0 + ai * HALF + m * 16;
;                 float ps = 0.f, pss = 0.f;
;                 f32x4 c0 = {1.f, 1.f, 1.f, 1.f}, c1 = c0, s0 = {0.f, 0.f, 0.f, 0.f}, s1 = s0;
;                 if (kind <= 1 && ropelane) { const f32x4* rp = (const f32x4*)(rope + (size_t)row * 16); c0 = rp[0]; c1 = rp[1]; s0 = rp[2]; s1 = rp[3]; }
.LBB0_1277:
	v_add_u32_e32 v50, 0xa0, v180
	v_ashrrev_i32_e32 v51, 31, v50
	s_waitcnt lgkmcnt(1)
	s_waitcnt lgkmcnt(0)
	s_cmp_lg_u32 s99, 0
	s_cbranch_scc1 .Lropedef_1_6
	v_mov_b32_e32 v38, 1.0
	v_mov_b32_e32 v34, 0
	v_mov_b32_e32 v35, v34
	v_mov_b32_e32 v36, v34
	v_mov_b32_e32 v37, v34
	v_mov_b32_e32 v42, v34
	v_mov_b32_e32 v43, v34
	v_mov_b32_e32 v44, v34
	v_mov_b32_e32 v45, v34
	v_mov_b32_e32 v39, v38
	v_mov_b32_e32 v40, v38
	v_mov_b32_e32 v41, v38
	v_mov_b32_e32 v46, v38
	v_mov_b32_e32 v47, v38
	v_mov_b32_e32 v48, v38
	v_mov_b32_e32 v49, v38
.Lropedef_1_6:
	s_and_saveexec_b64 s[22:23], s[92:93]
	s_cbranch_execz .LBB0_1279
	v_lshlrev_b64 v[34:35], 6, v[50:51]
	v_lshl_add_u64 v[46:47], s[40:41], 0, v[34:35]
	global_load_dwordx4 v[34:37], v[46:47], off offset:48
	global_load_dwordx4 v[42:45], v[46:47], off offset:32
	global_load_dwordx4 v[38:41], v[46:47], off offset:16
	s_nop 0
	global_load_dwordx4 v[46:49], v[46:47], off

;     __device__ __forceinline__ void operator()(const f32x4 (&acc)[2][2][4][2], const Unit& u, int wr, int wc, int fr, int fq) const {
;     ...
;                 const int row = row0 + ai * HALF + m * 16;
;                 float ps = 0.f, pss = 0.f;
;                 f32x4 c0 = {1.f, 1.f, 1.f, 1.f}, c1 = c0, s0 = {0.f, 0.f, 0.f, 0.f}, s1 = s0;
;                 if (kind <= 1 && ropelane) { const f32x4* rp = (const f32x4*)(rope + (size_t)row * 16); c0 = rp[0]; c1 = rp[1]; s0 = rp[2]; s1 = rp[3]; }
.LBB0_1304:
	v_add_u32_e32 v34, 0xb0, v180
	v_ashrrev_i32_e32 v35, 31, v34
	s_waitcnt lgkmcnt(1)
	s_waitcnt lgkmcnt(0)
	s_cmp_lg_u32 s99, 0
	s_cbranch_scc1 .Lropedef_1_7
	v_mov_b32_e32 v22, 1.0
	v_mov_b32_e32 v18, 0
	v_mov_b32_e32 v19, v18
	v_mov_b32_e32 v20, v18
	v_mov_b32_e32 v21, v18
	v_mov_b32_e32 v26, v18
	v_mov_b32_e32 v27, v18
	v_mov_b32_e32 v28, v18
	v_mov_b32_e32 v29, v18
	v_mov_b32_e32 v23, v22
	v_mov_b32_e32 v24, v22
	v_mov_b32_e32 v25, v22
	v_mov_b32_e32 v30, v22
	v_mov_b32_e32 v31, v22
	v_mov_b32_e32 v32, v22
	v_mov_b32_e32 v33, v22
.Lropedef_1_7:
	s_and_saveexec_b64 s[22:23], s[92:93]
	s_cbranch_execz .LBB0_1306
	v_lshlrev_b64 v[18:19], 6, v[34:35]
	v_lshl_add_u64 v[30:31], s[40:41], 0, v[18:19]
	global_load_dwordx4 v[18:21], v[30:31], off offset:48
	global_load_dwordx4 v[26:29], v[30:31], off offset:32
	global_load_dwordx4 v[22:25], v[30:31], off offset:16
	s_nop 0
	global_load_dwordx4 v[30:33], v[30:31], off
